# v30 + leaders skip the L2 write-back at the FFN-in->FFN-out barrier in overlap mode (pass-1 ACT is consumed on the producer's XCD; guarded by an XCC-id==blockIdx&7 census)
# baseline (speedup 1.0000x reference)
_Z8mega_fwd4Args:
	s_add_u32 s12, s0, 0xe8
	v_and_b32_e32 v226, 0x3ff, v0
	s_addc_u32 s13, s1, 0
	v_cmp_gt_u32_e32 vcc, 64, v226
	s_and_saveexec_b64 s[4:5], vcc
	v_lshl_add_u32 v1, v226, 2, 0
	v_add_u32_e32 v1, 0x20000, v1
	v_mov_b32_e32 v2, 0
	ds_write_b32 v1, v2
	s_or_b64 exec, exec, s[4:5]
	s_load_dwordx2 s[66:67], s[0:1], 0xe8
	s_load_dword s68, s[0:1], 0xf0
	s_mov_b64 s[8:9], s[0:1]
	s_waitcnt lgkmcnt(0)
	s_barrier
	s_getreg_b32 s3, hwreg(HW_REG_XCC_ID, 0, 4)
	v_cmp_eq_u32_e64 s[78:79], 0, v226
	s_and_saveexec_b64 s[6:7], s[78:79]
	s_cbranch_execz .LBB0_5
	s_mov_b64 s[14:15], exec
	v_mbcnt_lo_u32_b32 v1, s14, 0
	v_mbcnt_hi_u32_b32 v1, s15, v1
	v_cmp_eq_u32_e32 vcc, 0, v1
	s_and_b64 s[4:5], exec, vcc
	s_mov_b64 exec, s[4:5]
	s_cbranch_execz .LBB0_5
	s_load_dwordx2 s[4:5], s[8:9], 0xe0
	s_xor_b32 s10, s3, s2
	s_and_b32 s10, s10, 7
	s_lshl_b32 s3, s3, 8
	s_and_b32 s3, s3, 0xf00
	v_mov_b32_e32 v1, 0x4000
	s_waitcnt lgkmcnt(0)
	s_add_u32 s4, s4, s3
	s_addc_u32 s5, s5, 0
	s_bcnt1_i32_b64 s3, s[14:15]
	v_mov_b32_e32 v2, s3
	global_atomic_add v1, v2, s[4:5] offset:1024
	s_cmp_eq_u32 s10, 0
	s_cbranch_scc1 .Lko_xl_ok
	s_load_dwordx2 s[10:11], s[8:9], 0xe0
	v_mov_b32_e32 v1, 0x9000
	s_waitcnt lgkmcnt(0)
	global_atomic_add v1, v2, s[10:11]
.Lko_xl_ok:
.LBB0_5:
	s_or_b64 exec, exec, s[6:7]
	v_mov_b32_e32 v18, v226
	s_mov_b64 s[4:5], s[0:1]
	s_load_dwordx2 s[14:15], s[4:5], 0xe0
	s_movk_i32 s4, 0xc00
	v_readfirstlane_b32 s3, v18
	v_cmp_gt_i32_e32 vcc, s4, v18
	s_and_saveexec_b64 s[6:7], vcc
	s_cbranch_execz .LBB0_12
	v_lshl_add_u32 v1, v18, 2, 0
	s_mov_b64 s[8:9], 0
	s_movk_i32 s4, 0x3ff
	s_movk_i32 s5, 0xfc00
	v_mov_b32_e32 v3, 0
	s_movk_i32 s10, 0x9ff
	v_mov_b32_e32 v6, v18
	s_branch .LBB0_8

.LBB0_1297:
	s_nop 0
	v_readlane_b32 s4, v253, 62
	s_cmp_ge_i32 s4, 0x97a0
	s_cselect_b32 s100, 1, 0
	s_cbranch_scc0 .Lko_entry_done
	s_add_i32 s101, s101, 1
	s_load_dwordx2 s[8:9], s[0:1], 0xe0
	s_waitcnt lgkmcnt(0)
	s_load_dword s4, s[8:9], 0x9000
	s_waitcnt lgkmcnt(0)
	s_nop 2
	v_writelane_b32 v255, s4, 62
	s_lshr_b32 s4, s2, 3
	s_mul_i32 s6, s4, 0xcccd
	s_lshr_b32 s6, s6, 18
	s_mul_i32 s8, s6, 5
	s_sub_i32 s4, s4, s8
	s_and_b32 s8, s2, 7
	s_mul_i32 s8, s8, 5
	s_add_i32 s4, s4, s8
	s_mov_b32 s8, 0
	s_nop 3
	v_writelane_b32 v253, s6, 36
	v_writelane_b32 v253, s4, 37
	v_writelane_b32 v253, s8, 38
	v_writelane_b32 v253, s6, 39
	v_writelane_b32 v253, s8, 40
	s_nop 1

.Lko_g1420:
	s_andn2_saveexec_b64 s[24:25], s[24:25]
	s_cbranch_execz .Lko_g1440
	s_mov_b64 s[24:25], exec
	s_cmp_eq_u32 s100, 0
	s_cbranch_scc1 .Lko_xl_wb_c
	v_readlane_b32 s26, v255, 62
	s_cmp_eq_u32 s26, 0
	s_cbranch_scc1 .Lko_xl_nowb_c
.Lko_xl_wb_c:
	buffer_wbl2 sc1
.Lko_xl_nowb_c:
	s_waitcnt vmcnt(0) lgkmcnt(0)
	s_waitcnt vmcnt(0)
	v_mbcnt_lo_u32_b32 v0, s24, 0
	v_mbcnt_hi_u32_b32 v0, s25, v0
	v_cmp_eq_u32_e32 vcc, 0, v0
	s_and_saveexec_b64 s[26:27], vcc
	s_cbranch_execz .Lko_g1423
	s_bcnt1_i32_b64 s4, s[24:25]
	v_mov_b32_e32 v3, s4
	v_mov_b32_e32 v4, 0x7000
	global_atomic_add v3, v4, v3, s[10:11] offset:1024 sc0
